# attention phases: one static s_setprio 1 for waves 4-7 at phase entry, reset before the gMLP units (strategy 4, static priority for the younger half)
# speedup vs baseline: 1.0042x; 1.0042x over previous
; __device__ __forceinline__ int v_st(int k, int c) { const int kk = (k & ~0xC) | ((k & 4) << 1) | ((k & 8) >> 1); return ((kk >> 3) * 4 + (c >> 5)) * 512 + ((kk & 7) * 32 + (c & 31)) * 2; }
; __device__ __forceinline__ void attn_dense_body(const bf16_t* __restrict__ Qb, const bf16_t* __restrict__ Kh, const bf16_t* __restrict__ Vh,
;                                                 bf16_t* __restrict__ Ob, int seq, char* lds, const int tid) {
;   constexpr int SDEPTH = ATT_SDEPTH;
;   const int wid = tid >> 6, lane = tid & 63, r32 = lane & 31, hi = lane >> 5;
;   bf16_t* V_lds = (bf16_t*)lds; bf16_t* K_lds = (bf16_t*)(lds + 2 * SHM_V);
;   float* ws = (float*)(lds + 2 * SHM_V + 2 * SHM_K) + wid * 64; float* li_l = ws; float* al_l = ws + 32;
;   float m_reg = -1e30f, l_reg = 0; f32x16 o[4] = {}; bf16x8 qr[8];
;   const bf16_t* Qw = Qb + (long)(wid * QBLK + r32) * LDQ + hi * 8;
; #pragma unroll
;   for (int d0 = 0; d0 < 8; ++d0) qr[d0] = ld8(Qw + d0 * 16);
;   const int sr = tid >> 4, sc = (tid & 15) * 8, vst0 = v_st(sr, sc), vst1 = v_st(32 + sr, sc);
;   const int vb0 = (int)(uintptr_t)V_lds + v_rd_base(lane);
;   struct { bf16x8 vs0, vs1, ks0, ks1; } sr_[SDEPTH];
;   const unsigned so0 = (unsigned)(sr * LDK + sc) * 2u, so1 = so0 + 32u * LDK * 2u;
; __device__ void phase_attn(const Ctx& c, int l, bool with_ctx, char* lds, bool skip_gmlp) {
;     const bf16_t* Qb = c.bfp(WS_Q); const bf16_t* Kb = c.bfp(WS_K); const bf16_t* Vb = c.bfp(WS_V); bf16_t* AM = c.bfp(WS_AM);
;     const int nun = with_ctx ? 576 : 512;
;     for (int i = 0; ; ++i) {
;         const int L = i * c.G + c.bid; if (L >= nun) break;
;         int b, h, seq; size_t qrow, kvrow;
;         if (L < 512) {
;             if (c.G == 256) { const int xcd = c.bid & 7, slot = c.bid >> 3, grp = i * 8 + xcd; b = grp >> 2; h = (grp & 3) * 4 + (slot >> 3); qrow = (size_t)b * SEQL + (slot & 7) * 256; }
;             else { b = L >> 7; h = (L >> 3) & 15; qrow = (size_t)b * SEQL + (L & 7) * 256; }
;             kvrow = (size_t)b * SKV; seq = SKV;
;         } else { const int u = L - 512; b = u >> 4; h = u & 15; qrow = (size_t)TL + b * CTXL; kvrow = (size_t)b * SKV + SEQL; seq = CTXL; }
;         const int kvh = h >> 2;
;         att::attn_dense_body(Qb + qrow * DM + h * 128, Kb + kvrow * 512 + kvh * 128, Vb + kvrow * 512 + kvh * 128,
.LBB0_432:
	s_mov_b32 s2, 0
	s_waitcnt lgkmcnt(0)
	s_barrier
	s_mov_b32 s3, s33
	v_mbcnt_lo_u32_b32 v0, -1, s2
	v_mbcnt_hi_u32_b32 v0, -1, v0
	v_lshl_or_b32 v194, s3, 6, v0
	v_readfirstlane_b32 s35, v217
	s_cmp_lt_u32 s33, 4
	s_cbranch_scc1 .Lprio_skip_1
	s_setprio 1
.Lprio_skip_1:
	s_mov_b64 s[2:3], s[0:1]
	s_load_dwordx2 s[8:9], s[2:3], 0xc0
	s_mov_b32 s17, 0
	s_waitcnt lgkmcnt(0)
	s_add_u32 s43, s8, 0x28978000
	s_addc_u32 s56, s9, 0
	s_cmpk_lt_i32 s35, 0x240
	s_cselect_b64 s[10:11], -1, 0
	s_cmpk_gt_i32 s35, 0x23f
	s_cbranch_scc1 .LBB0_462
	s_add_u32 s57, s8, 0x2d178000
	s_addc_u32 s58, s9, 0
	s_add_u32 s59, s8, 0x2f578000
	s_addc_u32 s60, s9, 0
	s_add_u32 s61, s8, 0x2fe78000
	s_addc_u32 s62, s9, 0
	v_and_b32_e32 v2, 0x3fffffc0, v194
	s_add_i32 s4, 0, 0x10000
	v_lshl_add_u32 v195, v2, 2, s4
	v_ashrrev_i32_e32 v3, 1, v194
	s_movk_i32 s4, 0xffe0
	v_and_b32_e32 v2, 0xffffffe0, v3
	v_bfi_b32 v4, s4, v3, v194
	v_ashrrev_i32_e32 v3, 4, v194
	v_add_u32_e32 v11, 32, v3
	v_ashrrev_i32_e32 v5, 31, v4
	v_and_b32_e32 v8, 0xfffff0, v3
	v_lshlrev_b32_e32 v9, 1, v3
	v_and_b32_e32 v12, 0xfffff0, v11
	v_lshlrev_b32_e32 v13, 1, v11
	v_lshlrev_b64 v[176:177], 12, v[4:5]
	v_lshlrev_b32_e32 v5, 3, v194
	v_and_or_b32 v8, v9, 8, v8
	v_and_or_b32 v12, v13, 8, v12
	v_and_b32_e32 v7, 0x78, v5
	v_lshrrev_b32_e32 v9, 1, v3
	v_lshrrev_b32_e32 v8, 1, v8
	v_bfe_u32 v5, v5, 5, 2
	v_and_b32_e32 v10, 3, v3
	v_lshrrev_b32_e32 v12, 1, v12
	v_or_b32_e32 v8, v8, v5
	v_and_or_b32 v9, v9, 4, v10
	v_lshlrev_b32_e32 v7, 1, v7
	v_or_b32_e32 v5, v12, v5
	v_lshlrev_b32_e32 v8, 9, v8
	v_lshlrev_b32_e32 v9, 6, v9
	v_and_b32_e32 v10, 48, v7
	v_lshlrev_b32_e32 v5, 9, v5
	v_and_b32_e32 v1, 63, v194
	v_or3_b32 v8, v8, v9, v10
	v_or3_b32 v5, v5, v9, v10
	v_lshlrev_b32_e32 v10, 4, v194
	v_lshlrev_b32_e32 v9, 3, v1
	v_and_b32_e32 v12, 0xc0, v10
	v_lshlrev_b32_e32 v13, 1, v194
	v_and_or_b32 v12, v9, 24, v12
	v_and_b32_e32 v13, 32, v13
	v_and_b32_e32 v9, 0x100, v9
	v_bfe_u32 v6, v194, 5, 1
	v_or3_b32 v9, v12, v13, v9
	s_cmp_lg_u32 0, -1
	v_lshl_or_b32 v180, v3, 10, v7
	v_lshlrev_b32_e32 v3, 8, v3
	v_and_b32_e32 v12, 0x70, v194
	v_and_b32_e32 v0, 31, v194
	s_cselect_b32 s6, 0, 0
	s_lshl_b32 s4, s35, 2
	v_bitop3_b32 v13, v7, v3, v12 bitop3:0xde
	v_lshlrev_b32_e32 v3, 8, v11
	v_lshlrev_b32_e32 v197, 4, v6
	s_and_b32 s65, s4, 12
	s_ashr_i32 s4, s35, 6
	v_bitop3_b32 v7, v7, v3, v12 bitop3:0xde
	v_lshlrev_b32_e32 v3, 8, v0
	v_and_b32_e32 v10, 0x70, v10
	v_or_b32_e32 v12, 32, v197
	v_or_b32_e32 v14, 64, v197
	v_or_b32_e32 v15, 0x60, v197
	v_or_b32_e32 v16, 0x80, v197
	v_or_b32_e32 v17, 0xa0, v197
	v_or_b32_e32 v18, 0xc0, v197
	v_or_b32_e32 v19, 0xe0, v197
	v_lshlrev_b32_e32 v4, 3, v6
	v_mov_b32_e32 v179, 0
	v_add_u32_e32 v196, s6, v9
	s_add_i32 s65, s65, s4
	s_lshl_b32 s4, s35, 5
	v_bitop3_b32 v11, v197, v3, v10 bitop3:0xde
	v_bitop3_b32 v12, v12, v3, v10 bitop3:0xde
	v_bitop3_b32 v14, v14, v3, v10 bitop3:0xde
	v_bitop3_b32 v15, v15, v3, v10 bitop3:0xde
	v_bitop3_b32 v16, v16, v3, v10 bitop3:0xde
	v_bitop3_b32 v17, v17, v3, v10 bitop3:0xde
	v_bitop3_b32 v18, v18, v3, v10 bitop3:0xde
	v_bitop3_b32 v10, v19, v3, v10 bitop3:0xde
	s_addk_i32 s6, 0x4000
	v_ashrrev_i32_e32 v3, 31, v2
	s_mov_b32 s63, 0x8000
	v_add_u32_e32 v182, 0x8000, v180
	v_mov_b32_e32 v181, v179
	v_mov_b32_e32 v183, v179
	s_and_b32 s64, s35, 4
	s_and_b32 s14, s4, 0x700
	s_mov_b32 s15, s17
	v_cmp_gt_u32_e64 s[4:5], 32, v1
	v_lshl_add_u32 v198, v0, 2, v195
	s_movk_i32 s66, 0x4000
	v_add_u32_e32 v199, s6, v9
	v_lshlrev_b64 v[184:185], 11, v[2:3]
	v_lshlrev_b32_e32 v186, 13, v6
	v_mov_b32_e32 v187, v179
	s_mov_b32 s67, 0x42b504f3
	s_mov_b32 s34, 0x3e0293ee
	s_mov_b32 s68, 0x2fea8000
	s_mov_b32 s69, 0x2f5a8000
	v_lshlrev_b32_e32 v178, 1, v0
	s_movk_i32 s70, 0x1000
	s_movk_i32 s71, 0x5000
	s_mov_b32 s72, 0x9000
	s_mov_b32 s73, 0xc000
	s_mov_b32 s74, 0xd000
	v_lshlrev_b32_e32 v188, 1, v4
	v_mov_b32_e32 v189, v179
	v_add_u32_e32 v200, 0, v8
	v_add_u32_e32 v201, 0, v5
	v_add_u32_e32 v202, 0, v13
	v_add_u32_e32 v203, 0, v7
	v_add_u32_e32 v204, 0, v11
	v_add_u32_e32 v205, 0, v12
	v_add_u32_e32 v206, 0, v14
	v_add_u32_e32 v207, 0, v15
	v_add_u32_e32 v208, 0, v16
	v_add_u32_e32 v209, 0, v17
	v_add_u32_e32 v210, 0, v18
	v_add_u32_e32 v211, 0, v10
	v_mov_b32_e32 v212, 0xf149f2ca
	s_mov_b32 s20, s35
	s_mov_b32 s75, 0
	s_branch .LBB0_435

; __device__ __forceinline__ unsigned cvt_pk_bf16(float lo, float hi) { unsigned r; asm volatile("v_cvt_pk_bf16_f32 %0, %1, %2" : "=v"(r) : "v"(lo), "v"(hi)); return r; }
; __device__ void gmlp_unit(const Ctx& c, int tid, int l, int ch, int g, unsigned short* T) {
;     const KParams pk = c.p;
;     const int lane = tid & 63, wave = tid >> 6;
;     const int r32 = lane & 31, hi = lane >> 5, pblk = wave >> 1, cb0 = (wave & 1) * 2;
;     const float* wsr = pk->in[10] + ((size_t)(l * 8 + g) * 128 + pblk * 32 + r32) * 128 + hi * 8;
;     const bf16_t* vn = c.bfp(WS_VN) + (size_t)(ch * 128) * 1024 + g * 128;
;     bf16_t* AM0 = c.bfp(WS_AM);
;     {
;         const int q = tid >> 4, c8 = (tid & 15) * 8;
;         u32x4 v[4];
; #pragma unroll
;         for (int ps = 0; ps < 4; ++ps) v[ps] = *(const u32x4*)(vn + (size_t)(q + 32 * ps) * 1024 + c8);
; #pragma unroll
;         for (int ps = 0; ps < 4; ++ps) { unsigned short* d = T + (q + 32 * ps) * 132 + c8; *(u32x2*)d = (u32x2){v[ps].x, v[ps].y}; *(u32x2*)(d + 4) = (u32x2){v[ps].z, v[ps].w}; }
;     }
;     bf16x8 af[8];
; #pragma unroll
;     for (int ks = 0; ks < 8; ++ks) { const f32x4 a0 = *(const f32x4*)(wsr + ks * 16), a1 = *(const f32x4*)(wsr + ks * 16 + 4);
;         u32x4 aw; aw.x = cvt_pk_bf16(a0[0], a0[1]); aw.y = cvt_pk_bf16(a0[2], a0[3]); aw.z = cvt_pk_bf16(a1[0], a1[1]); aw.w = cvt_pk_bf16(a1[2], a1[3]);
;         af[ks] = *reinterpret_cast<const bf16x8*>(&aw); }
;     __syncthreads();
;     f32x16 acc0 = {}, acc1 = {};
;     const unsigned short* tb = T + (hi * 8) * 132 + cb0 * 32 + r32;
; #pragma unroll
;     for (int ks = 0; ks < 8; ++ks) {
;         bf16x8 b0, b1;
; #pragma unroll
;         for (int j = 0; j < 8; ++j) { b0[j] = (short)tb[(ks * 16 + j) * 132]; b1[j] = (short)tb[(ks * 16 + j) * 132 + 32]; }
;         acc0 = __builtin_amdgcn_mfma_f32_32x32x16_bf16(af[ks], b0, acc0, 0, 0, 0);
;         acc1 = __builtin_amdgcn_mfma_f32_32x32x16_bf16(af[ks], b1, acc1, 0, 0, 0); }
; #pragma unroll
;     for (int r = 0; r < 16; ++r) { const int prow = pblk * 32 + att::crow(r, hi); const size_t t = (size_t)ch * 128 + prow;
;         const float bias = pk->in[11][(l * 8 + g) * 128 + prow];
;         bf16_t* up = AM0 + t * 1024 + g * 128 + cb0 * 32 + r32;
;         up[0] = f2bf(bf2f(up[0]) * (acc0[r] + bias)); up[32] = f2bf(bf2f(up[32]) * (acc1[r] + bias)); }
.LBB0_462:
	s_setprio 0
	s_sub_i32 s35, s38, s35
	s_add_i32 s35, s35, -1
	s_andn2_b64 vcc, exec, s[10:11]
	s_cbranch_vccnz .LBB0_465
	v_ashrrev_i32_e32 v2, 2, v194
	v_and_b32_e32 v5, 0xffffffe0, v2
	v_ashrrev_i32_e32 v2, 4, v194
	v_lshlrev_b32_e32 v3, 3, v194
	v_and_b32_e32 v4, 0x78, v3
	v_ashrrev_i32_e32 v3, 31, v2
	v_lshlrev_b64 v[36:37], 11, v[2:3]
	s_mov_b64 s[4:5], 0x10000
	v_lshl_add_u64 v[38:39], v[36:37], 0, s[4:5]
	s_mov_b64 s[4:5], 0x20000
	v_lshl_add_u64 v[40:41], v[36:37], 0, s[4:5]
	s_mov_b64 s[4:5], 0x30000
	v_lshl_add_u64 v[42:43], v[36:37], 0, s[4:5]
	s_movk_i32 s4, 0x108
	v_and_b32_e32 v0, 31, v194
	v_bfe_u32 v1, v194, 5, 1
	v_mul_lo_u32 v8, v2, s4
	v_and_b32_e32 v2, 64, v194
	s_movk_i32 s4, 0x840
	v_mad_u32_u24 v6, v1, s4, 0
	v_lshlrev_b32_e32 v7, 1, v2
	v_lshlrev_b32_e32 v9, 1, v0
	v_lshl_or_b32 v44, v1, 2, v5
	v_add3_u32 v90, v6, v7, v9
	v_or_b32_e32 v6, 1, v44
	v_ashrrev_i32_e32 v7, 31, v6
	v_lshlrev_b64 v[48:49], 11, v[6:7]
	v_or_b32_e32 v6, 2, v44
	v_ashrrev_i32_e32 v7, 31, v6
	v_lshlrev_b64 v[50:51], 11, v[6:7]
	v_or_b32_e32 v6, 3, v44
	v_ashrrev_i32_e32 v7, 31, v6
	v_lshlrev_b64 v[52:53], 11, v[6:7]
	v_or_b32_e32 v6, 8, v44
	v_ashrrev_i32_e32 v7, 31, v6
	v_lshlrev_b64 v[54:55], 11, v[6:7]
	v_or_b32_e32 v6, 9, v44
	v_ashrrev_i32_e32 v7, 31, v6
	v_lshlrev_b64 v[56:57], 11, v[6:7]
	v_or_b32_e32 v6, 10, v44
	v_ashrrev_i32_e32 v7, 31, v6
	v_lshlrev_b64 v[58:59], 11, v[6:7]
	v_or_b32_e32 v6, 11, v44
	v_ashrrev_i32_e32 v7, 31, v6
	v_lshlrev_b64 v[60:61], 11, v[6:7]
	v_or_b32_e32 v6, 16, v44
	v_ashrrev_i32_e32 v7, 31, v6
	v_lshlrev_b64 v[62:63], 11, v[6:7]
	v_or_b32_e32 v6, 17, v44
	v_ashrrev_i32_e32 v7, 31, v6
	v_lshlrev_b64 v[64:65], 11, v[6:7]
	v_or_b32_e32 v6, 18, v44
	v_ashrrev_i32_e32 v7, 31, v6
	v_lshlrev_b64 v[66:67], 11, v[6:7]
	v_or_b32_e32 v6, 19, v44
	v_ashrrev_i32_e32 v7, 31, v6
	v_lshlrev_b64 v[68:69], 11, v[6:7]
	v_or_b32_e32 v6, 24, v44
	v_ashrrev_i32_e32 v7, 31, v6
	v_lshlrev_b64 v[70:71], 11, v[6:7]
	v_or_b32_e32 v6, 25, v44
	v_ashrrev_i32_e32 v7, 31, v6
	s_load_dwordx2 s[6:7], s[2:3], 0x50
	v_lshlrev_b64 v[72:73], 11, v[6:7]
	v_or_b32_e32 v6, 26, v44
	v_ashrrev_i32_e32 v7, 31, v6
	v_lshlrev_b64 v[74:75], 11, v[6:7]
	v_or_b32_e32 v6, 27, v44
	v_mov_b32_e32 v35, 0
	v_lshl_add_u32 v3, v4, 1, 0
	v_ashrrev_i32_e32 v45, 31, v44
	v_ashrrev_i32_e32 v7, 31, v6
	s_add_u32 s8, s8, 0x30778000
	v_lshlrev_b32_e32 v34, 5, v1
	v_ashrrev_i32_e32 v33, 31, v5
	v_or_b32_e32 v32, v5, v0
	s_mov_b32 s5, 0
	v_lshlrev_b64 v[46:47], 11, v[44:45]
	v_lshlrev_b64 v[76:77], 11, v[6:7]
	s_addc_u32 s9, s9, 0
	s_waitcnt lgkmcnt(0)
	v_lshl_add_u64 v[78:79], s[6:7], 0, v[34:35]
	s_lshl_b32 s10, s35, 7
	s_lshl_b32 s11, s38, 7
	v_lshlrev_b32_e32 v34, 1, v4
	v_add_u32_e32 v45, v3, v8
	s_mov_b32 s14, 0x5040100
	v_lshlrev_b32_e32 v80, 1, v2
	v_lshlrev_b32_e32 v82, 1, v0

; __device__ __forceinline__ int v_st(int k, int c) { const int kk = (k & ~0xC) | ((k & 4) << 1) | ((k & 8) >> 1); return ((kk >> 3) * 4 + (c >> 5)) * 512 + ((kk & 7) * 32 + (c & 31)) * 2; }
; __device__ __forceinline__ int v_rd_base(int lane) { return ((lane & 3) << 3) | (((lane >> 2) & 3) << 6) | (((lane >> 4) & 1) << 5) | (((lane >> 5) & 1) << 8); }
; __device__ __forceinline__ void attn_dense_body(const bf16_t* __restrict__ Qb, const bf16_t* __restrict__ Kh, const bf16_t* __restrict__ Vh,
;                                                 bf16_t* __restrict__ Ob, int seq, char* lds, const int tid) {
;   constexpr int SDEPTH = ATT_SDEPTH;
;   const int wid = tid >> 6, lane = tid & 63, r32 = lane & 31, hi = lane >> 5;
;   bf16_t* V_lds = (bf16_t*)lds; bf16_t* K_lds = (bf16_t*)(lds + 2 * SHM_V);
;   float* ws = (float*)(lds + 2 * SHM_V + 2 * SHM_K) + wid * 64; float* li_l = ws; float* al_l = ws + 32;
;   float m_reg = -1e30f, l_reg = 0; f32x16 o[4] = {}; bf16x8 qr[8];
;   const bf16_t* Qw = Qb + (long)(wid * QBLK + r32) * LDQ + hi * 8;
; #pragma unroll
;   for (int d0 = 0; d0 < 8; ++d0) qr[d0] = ld8(Qw + d0 * 16);
;   const int sr = tid >> 4, sc = (tid & 15) * 8, vst0 = v_st(sr, sc), vst1 = v_st(32 + sr, sc);
;   const int vb0 = (int)(uintptr_t)V_lds + v_rd_base(lane);
;   struct { bf16x8 vs0, vs1, ks0, ks1; } sr_[SDEPTH];
;   const unsigned so0 = (unsigned)(sr * LDK + sc) * 2u, so1 = so0 + 32u * LDK * 2u;
; __device__ void phase_attn(const Ctx& c, int l, bool with_ctx, char* lds, bool skip_gmlp) {
;     const bf16_t* Qb = c.bfp(WS_Q); const bf16_t* Kb = c.bfp(WS_K); const bf16_t* Vb = c.bfp(WS_V); bf16_t* AM = c.bfp(WS_AM);
;     const int nun = with_ctx ? 576 : 512;
;     for (int i = 0; ; ++i) {
;         const int L = i * c.G + c.bid; if (L >= nun) break;
;         int b, h, seq; size_t qrow, kvrow;
;         if (L < 512) {
;             if (c.G == 256) { const int xcd = c.bid & 7, slot = c.bid >> 3, grp = i * 8 + xcd; b = grp >> 2; h = (grp & 3) * 4 + (slot >> 3); qrow = (size_t)b * SEQL + (slot & 7) * 256; }
;             else { b = L >> 7; h = (L >> 3) & 15; qrow = (size_t)b * SEQL + (L & 7) * 256; }
;             kvrow = (size_t)b * SKV; seq = SKV;
;         } else { const int u = L - 512; b = u >> 4; h = u & 15; qrow = (size_t)TL + b * CTXL; kvrow = (size_t)b * SKV + SEQL; seq = CTXL; }
;         const int kvh = h >> 2;
.Lprio_skip_0:
	s_mov_b64 s[2:3], s[0:1]
	s_load_dwordx2 s[8:9], s[2:3], 0xc0
	s_mov_b32 s16, 0
	s_waitcnt lgkmcnt(0)
	s_add_u32 s50, s8, 0x28978000
	s_addc_u32 s51, s9, 0
	s_cmpk_lt_i32 s35, 0x200
	s_cselect_b64 s[10:11], -1, 0
	s_cmpk_gt_i32 s35, 0x1ff
	s_cbranch_scc1 .LBB0_1542
	s_add_u32 s52, s8, 0x2d178000
	s_addc_u32 s53, s9, 0
	s_add_u32 s54, s8, 0x2f578000
	s_addc_u32 s55, s9, 0
	s_add_u32 s56, s8, 0x2fe78000
	s_addc_u32 s57, s9, 0
	v_and_b32_e32 v2, 0x3fffffc0, v194
	s_add_i32 s4, 0, 0x10000
	v_lshl_add_u32 v195, v2, 2, s4
	v_ashrrev_i32_e32 v3, 1, v194
	s_movk_i32 s4, 0xffe0
	v_and_b32_e32 v2, 0xffffffe0, v3
	v_bfi_b32 v4, s4, v3, v194
	v_ashrrev_i32_e32 v3, 4, v194
	v_add_u32_e32 v11, 32, v3
	v_ashrrev_i32_e32 v5, 31, v4
	v_and_b32_e32 v8, 0xfffff0, v3
	v_lshlrev_b32_e32 v9, 1, v3
	v_and_b32_e32 v12, 0xfffff0, v11
	v_lshlrev_b32_e32 v13, 1, v11
	v_lshlrev_b64 v[176:177], 12, v[4:5]
	v_lshlrev_b32_e32 v5, 3, v194
	v_and_or_b32 v8, v9, 8, v8
	v_and_or_b32 v12, v13, 8, v12
	v_and_b32_e32 v7, 0x78, v5
	v_lshrrev_b32_e32 v9, 1, v3
	v_lshrrev_b32_e32 v8, 1, v8
	v_bfe_u32 v5, v5, 5, 2
	v_and_b32_e32 v10, 3, v3
	v_lshrrev_b32_e32 v12, 1, v12
	v_or_b32_e32 v8, v8, v5
	v_and_or_b32 v9, v9, 4, v10
	v_lshlrev_b32_e32 v7, 1, v7
	v_or_b32_e32 v5, v12, v5
	v_lshlrev_b32_e32 v8, 9, v8
	v_lshlrev_b32_e32 v9, 6, v9
	v_and_b32_e32 v10, 48, v7
	v_lshlrev_b32_e32 v5, 9, v5
	v_and_b32_e32 v1, 63, v194
	v_or3_b32 v8, v8, v9, v10
	v_or3_b32 v5, v5, v9, v10
	v_lshlrev_b32_e32 v10, 4, v194
	v_lshlrev_b32_e32 v9, 3, v1
	v_and_b32_e32 v12, 0xc0, v10
	v_lshlrev_b32_e32 v13, 1, v194
	v_and_or_b32 v12, v9, 24, v12
	v_and_b32_e32 v13, 32, v13
	v_and_b32_e32 v9, 0x100, v9
	v_bfe_u32 v6, v194, 5, 1
	v_or3_b32 v9, v12, v13, v9
	s_cmp_lg_u32 0, -1
	v_lshl_or_b32 v180, v3, 10, v7
	v_lshlrev_b32_e32 v3, 8, v3
	v_and_b32_e32 v12, 0x70, v194
	v_and_b32_e32 v0, 31, v194
	s_cselect_b32 s6, 0, 0
	s_lshl_b32 s4, s35, 2
	v_bitop3_b32 v13, v7, v3, v12 bitop3:0xde
	v_lshlrev_b32_e32 v3, 8, v11
	v_lshlrev_b32_e32 v197, 4, v6
	s_and_b32 s60, s4, 12
	s_ashr_i32 s4, s35, 6
	v_bitop3_b32 v7, v7, v3, v12 bitop3:0xde
	v_lshlrev_b32_e32 v3, 8, v0
	v_and_b32_e32 v10, 0x70, v10
	v_or_b32_e32 v12, 32, v197
	v_or_b32_e32 v14, 64, v197
	v_or_b32_e32 v15, 0x60, v197
	v_or_b32_e32 v16, 0x80, v197
	v_or_b32_e32 v17, 0xa0, v197
	v_or_b32_e32 v18, 0xc0, v197
	v_or_b32_e32 v19, 0xe0, v197
	v_lshlrev_b32_e32 v4, 3, v6
	v_mov_b32_e32 v179, 0
	v_add_u32_e32 v196, s6, v9
	s_add_i32 s60, s60, s4
	s_lshl_b32 s4, s35, 5
	v_bitop3_b32 v11, v197, v3, v10 bitop3:0xde
	v_bitop3_b32 v12, v12, v3, v10 bitop3:0xde
	v_bitop3_b32 v14, v14, v3, v10 bitop3:0xde
	v_bitop3_b32 v15, v15, v3, v10 bitop3:0xde
	v_bitop3_b32 v16, v16, v3, v10 bitop3:0xde
	v_bitop3_b32 v17, v17, v3, v10 bitop3:0xde
	v_bitop3_b32 v18, v18, v3, v10 bitop3:0xde
	v_bitop3_b32 v10, v19, v3, v10 bitop3:0xde
	s_addk_i32 s6, 0x4000
	v_ashrrev_i32_e32 v3, 31, v2
	s_mov_b32 s58, 0x8000
	v_add_u32_e32 v182, 0x8000, v180
	v_mov_b32_e32 v181, v179
	v_mov_b32_e32 v183, v179
	s_and_b32 s59, s35, 4
	s_and_b32 s14, s4, 0x700
	s_mov_b32 s15, s16
	v_cmp_gt_u32_e64 s[4:5], 32, v1
	v_lshl_add_u32 v198, v0, 2, v195
	s_movk_i32 s61, 0x4000
	v_add_u32_e32 v199, s6, v9
	v_lshlrev_b64 v[184:185], 11, v[2:3]
	v_lshlrev_b32_e32 v186, 13, v6
	v_mov_b32_e32 v187, v179
	s_mov_b32 s62, 0x42b504f3
	s_mov_b32 s34, 0x3e0293ee
	s_mov_b32 s63, 0x2fea8000
	s_mov_b32 s64, 0x2f5a8000
	v_lshlrev_b32_e32 v178, 1, v0
	s_movk_i32 s65, 0x1000
	s_movk_i32 s66, 0x5000
	s_mov_b32 s67, 0x9000
	s_mov_b32 s68, 0xc000
	s_mov_b32 s69, 0xd000
	v_lshlrev_b32_e32 v188, 1, v4
	v_mov_b32_e32 v189, v179
	v_add_u32_e32 v200, 0, v8
	v_add_u32_e32 v201, 0, v5
	v_add_u32_e32 v202, 0, v13
	v_add_u32_e32 v203, 0, v7
	v_add_u32_e32 v204, 0, v11
	v_add_u32_e32 v205, 0, v12
	v_add_u32_e32 v206, 0, v14
	v_add_u32_e32 v207, 0, v15
	v_add_u32_e32 v208, 0, v16
	v_add_u32_e32 v209, 0, v17
	v_add_u32_e32 v210, 0, v18
	v_add_u32_e32 v211, 0, v10
	v_mov_b32_e32 v212, 0xf149f2ca
	s_mov_b32 s17, s35
	s_mov_b32 s70, 0
	s_branch .LBB0_1519

; __device__ __forceinline__ unsigned cvt_pk_bf16(float lo, float hi) { unsigned r; asm volatile("v_cvt_pk_bf16_f32 %0, %1, %2" : "=v"(r) : "v"(lo), "v"(hi)); return r; }
; __device__ void gmlp_unit(const Ctx& c, int tid, int l, int ch, int g, unsigned short* T) {
;     const KParams pk = c.p;
;     const int lane = tid & 63, wave = tid >> 6;
;     const int r32 = lane & 31, hi = lane >> 5, pblk = wave >> 1, cb0 = (wave & 1) * 2;
;     const float* wsr = pk->in[10] + ((size_t)(l * 8 + g) * 128 + pblk * 32 + r32) * 128 + hi * 8;
;     const bf16_t* vn = c.bfp(WS_VN) + (size_t)(ch * 128) * 1024 + g * 128;
;     bf16_t* AM0 = c.bfp(WS_AM);
;     {
;         const int q = tid >> 4, c8 = (tid & 15) * 8;
;         u32x4 v[4];
; #pragma unroll
;         for (int ps = 0; ps < 4; ++ps) v[ps] = *(const u32x4*)(vn + (size_t)(q + 32 * ps) * 1024 + c8);
; #pragma unroll
;         for (int ps = 0; ps < 4; ++ps) { unsigned short* d = T + (q + 32 * ps) * 132 + c8; *(u32x2*)d = (u32x2){v[ps].x, v[ps].y}; *(u32x2*)(d + 4) = (u32x2){v[ps].z, v[ps].w}; }
;     }
;     bf16x8 af[8];
; #pragma unroll
;     for (int ks = 0; ks < 8; ++ks) { const f32x4 a0 = *(const f32x4*)(wsr + ks * 16), a1 = *(const f32x4*)(wsr + ks * 16 + 4);
;         u32x4 aw; aw.x = cvt_pk_bf16(a0[0], a0[1]); aw.y = cvt_pk_bf16(a0[2], a0[3]); aw.z = cvt_pk_bf16(a1[0], a1[1]); aw.w = cvt_pk_bf16(a1[2], a1[3]);
;         af[ks] = *reinterpret_cast<const bf16x8*>(&aw); }
;     __syncthreads();
;     f32x16 acc0 = {}, acc1 = {};
;     const unsigned short* tb = T + (hi * 8) * 132 + cb0 * 32 + r32;
; #pragma unroll
;     for (int ks = 0; ks < 8; ++ks) {
;         bf16x8 b0, b1;
; #pragma unroll
;         for (int j = 0; j < 8; ++j) { b0[j] = (short)tb[(ks * 16 + j) * 132]; b1[j] = (short)tb[(ks * 16 + j) * 132 + 32]; }
;         acc0 = __builtin_amdgcn_mfma_f32_32x32x16_bf16(af[ks], b0, acc0, 0, 0, 0);
;         acc1 = __builtin_amdgcn_mfma_f32_32x32x16_bf16(af[ks], b1, acc1, 0, 0, 0); }
; #pragma unroll
;     for (int r = 0; r < 16; ++r) { const int prow = pblk * 32 + att::crow(r, hi); const size_t t = (size_t)ch * 128 + prow;
;         const float bias = pk->in[11][(l * 8 + g) * 128 + prow];
;         bf16_t* up = AM0 + t * 1024 + g * 128 + cb0 * 32 + r32;
;         up[0] = f2bf(bf2f(up[0]) * (acc0[r] + bias)); up[32] = f2bf(bf2f(up[32]) * (acc1[r] + bias)); }
.LBB0_1542:
	s_setprio 0
	s_andn2_b64 vcc, exec, s[10:11]
	s_cbranch_vccnz .LBB0_1545
	v_ashrrev_i32_e32 v2, 2, v194
	v_and_b32_e32 v5, 0xffffffe0, v2
	v_ashrrev_i32_e32 v2, 4, v194
	v_lshlrev_b32_e32 v3, 3, v194
	v_and_b32_e32 v4, 0x78, v3
	v_ashrrev_i32_e32 v3, 31, v2
	v_lshlrev_b64 v[36:37], 11, v[2:3]
	s_mov_b64 s[4:5], 0x10000
	v_lshl_add_u64 v[38:39], v[36:37], 0, s[4:5]
	s_mov_b64 s[4:5], 0x20000
	s_load_dwordx2 s[6:7], s[2:3], 0x50
	v_bfe_u32 v1, v194, 5, 1
	v_lshl_add_u64 v[40:41], v[36:37], 0, s[4:5]
	s_mov_b64 s[4:5], 0x30000
	v_lshl_add_u64 v[42:43], v[36:37], 0, s[4:5]
	s_movk_i32 s4, 0x108
	v_lshl_or_b32 v44, v1, 2, v5
	v_and_b32_e32 v0, 31, v194
	v_mul_lo_u32 v6, v2, s4
	v_and_b32_e32 v2, 64, v194
	s_movk_i32 s4, 0x840
	v_or_b32_e32 v48, 1, v44
	v_or_b32_e32 v52, 2, v44
	v_or_b32_e32 v56, 3, v44
	v_or_b32_e32 v60, 8, v44
	v_or_b32_e32 v64, 9, v44
	v_or_b32_e32 v68, 10, v44
	v_or_b32_e32 v72, 11, v44
	v_or_b32_e32 v76, 16, v44
	v_or_b32_e32 v80, 17, v44
	v_or_b32_e32 v84, 18, v44
	v_or_b32_e32 v88, 19, v44
	v_or_b32_e32 v92, 24, v44
	v_or_b32_e32 v96, 25, v44
	v_or_b32_e32 v100, 26, v44
	v_or_b32_e32 v104, 27, v44
	v_mov_b32_e32 v35, 0
	v_lshl_add_u32 v3, v4, 1, 0
	v_mad_u32_u24 v7, v1, s4, 0
	v_lshlrev_b32_e32 v8, 1, v2
	v_lshlrev_b32_e32 v9, 1, v0
	v_ashrrev_i32_e32 v45, 31, v44
	v_ashrrev_i32_e32 v49, 31, v48
	v_ashrrev_i32_e32 v53, 31, v52
	v_ashrrev_i32_e32 v57, 31, v56
	v_ashrrev_i32_e32 v61, 31, v60
	v_ashrrev_i32_e32 v65, 31, v64
	v_ashrrev_i32_e32 v69, 31, v68
	v_ashrrev_i32_e32 v73, 31, v72
	v_ashrrev_i32_e32 v77, 31, v76
	v_ashrrev_i32_e32 v81, 31, v80
	v_ashrrev_i32_e32 v85, 31, v84
	v_ashrrev_i32_e32 v89, 31, v88
	v_ashrrev_i32_e32 v93, 31, v92
	v_ashrrev_i32_e32 v97, 31, v96
	v_ashrrev_i32_e32 v101, 31, v100
	v_ashrrev_i32_e32 v105, 31, v104
	s_add_u32 s8, s8, 0x30778000
	v_lshlrev_b32_e32 v34, 5, v1
	v_ashrrev_i32_e32 v33, 31, v5
	v_or_b32_e32 v32, v5, v0
	s_mov_b32 s5, 0
	v_add3_u32 v120, v7, v8, v9
	v_lshlrev_b64 v[46:47], 11, v[44:45]
	v_lshlrev_b64 v[50:51], 11, v[48:49]
	v_lshlrev_b64 v[54:55], 11, v[52:53]
	v_lshlrev_b64 v[58:59], 11, v[56:57]
	v_lshlrev_b64 v[62:63], 11, v[60:61]
	v_lshlrev_b64 v[66:67], 11, v[64:65]
	v_lshlrev_b64 v[70:71], 11, v[68:69]
	v_lshlrev_b64 v[74:75], 11, v[72:73]
	v_lshlrev_b64 v[78:79], 11, v[76:77]
	v_lshlrev_b64 v[82:83], 11, v[80:81]
	v_lshlrev_b64 v[86:87], 11, v[84:85]
	v_lshlrev_b64 v[90:91], 11, v[88:89]
	v_lshlrev_b64 v[94:95], 11, v[92:93]
	v_lshlrev_b64 v[98:99], 11, v[96:97]
	v_lshlrev_b64 v[102:103], 11, v[100:101]
	v_lshlrev_b64 v[106:107], 11, v[104:105]
	s_addc_u32 s9, s9, 0
	s_waitcnt lgkmcnt(0)
	v_lshl_add_u64 v[108:109], s[6:7], 0, v[34:35]
	s_lshl_b32 s10, s35, 7
	s_lshl_b32 s11, s38, 7
	v_lshlrev_b32_e32 v34, 1, v4
	v_add_u32_e32 v45, v3, v6
	s_mov_b32 s14, 0x5040100
	v_lshlrev_b32_e32 v110, 1, v2
	v_lshlrev_b32_e32 v112, 1, v0
